# P4 out-proj GEMM K-loop rewritten: n-major software-pipelined fragment reads, counted lgkmcnt, LDS-DMA issued right after barrier
# speedup vs baseline: 1.0084x; 1.0084x over previous
.LBB0_620:
	s_ashr_i32 s61, s85, 6
	v_mov_b32_e32 v10, v156
	s_and_b32 s62, s84, 63
	s_and_b32 s63, s85, 63
	s_lshl_b32 s58, s61, 8
	s_lshl_b32 s0, s62, 20
	v_ashrrev_i32_e32 v0, 3, v10
	s_ashr_i32 s59, s58, 31
	s_lshl_b32 s4, s63, 20
	v_xor_b32_e32 v6, v0, v10
	v_ashrrev_i32_e32 v1, 31, v0
	s_add_u32 s4, s24, s4
	v_lshlrev_b64 v[2:3], 12, v[0:1]
	v_lshlrev_b32_e32 v1, 4, v6
	s_addc_u32 s5, s25, 0
	s_lshl_b64 s[64:65], s[58:59], 12
	v_and_b32_e32 v132, 0x70, v1
	v_lshlrev_b32_e32 v1, 4, v10
	s_add_u32 s66, s16, s64
	v_add_u32_e32 v141, 0, v1
	s_addc_u32 s67, s17, s65
	v_lshl_add_u64 v[4:5], s[4:5], 0, v[2:3]
	v_add_u32_e32 v142, s8, v1
	v_readfirstlane_b32 s4, v141
	v_lshl_add_u64 v[4:5], v[4:5], 0, v[132:133]
	v_lshl_add_u64 v[6:7], s[66:67], 0, v[2:3]
	s_mov_b32 m0, s4
	v_readfirstlane_b32 s4, v142
	v_add_u32_e32 v1, 0x2000, v141
	v_lshl_add_u64 v[6:7], v[6:7], 0, v[132:133]
	s_barrier
	global_load_lds_dwordx4 v[4:5], off
	s_mov_b32 m0, s4
	v_readfirstlane_b32 s4, v1
	v_add_u32_e32 v1, 0x2000, v142
	global_load_lds_dwordx4 v[6:7], off
	v_lshl_add_u64 v[8:9], v[4:5], 0, s[6:7]
	s_mov_b32 m0, s4
	v_readfirstlane_b32 s4, v1
	v_add_u32_e32 v1, 0x4000, v141
	global_load_lds_dwordx4 v[8:9], off
	v_lshl_add_u64 v[8:9], v[6:7], 0, s[6:7]
	s_mov_b32 m0, s4
	v_readfirstlane_b32 s4, v1
	v_add_u32_e32 v1, 0x4000, v142
	global_load_lds_dwordx4 v[8:9], off
	v_lshl_add_u64 v[8:9], v[4:5], 0, s[18:19]
	s_mov_b32 m0, s4
	v_readfirstlane_b32 s4, v1
	v_add_u32_e32 v1, 0x6000, v141
	global_load_lds_dwordx4 v[8:9], off
	v_lshl_add_u64 v[8:9], v[6:7], 0, s[18:19]
	s_mov_b32 m0, s4
	v_readfirstlane_b32 s4, v1
	v_add_u32_e32 v1, 0x6000, v142
	global_load_lds_dwordx4 v[8:9], off
	v_lshl_add_u64 v[4:5], v[4:5], 0, s[26:27]
	s_mov_b32 m0, s4
	v_readfirstlane_b32 s4, v1
	global_load_lds_dwordx4 v[4:5], off
	v_lshl_add_u64 v[4:5], v[6:7], 0, s[26:27]
	s_mov_b32 m0, s4
	v_ashrrev_i32_e32 v1, 1, v10
	global_load_lds_dwordx4 v[4:5], off
	v_and_b32_e32 v135, 15, v10
	v_and_b32_e32 v136, 0xffffffc0, v1
	v_lshrrev_b32_e32 v11, 4, v10
	v_or_b32_e32 v1, v136, v135
	v_and_b32_e32 v6, 7, v10
	v_bfe_u32 v134, v10, 6, 1
	v_bfe_u32 v132, v10, 4, 2
	v_lshl_add_u32 v137, v1, 7, 0
	v_bitop3_b32 v1, v11, v6, 3 bitop3:0x6c
	v_lshlrev_b32_e32 v4, 13, v134
	v_lshlrev_b32_e32 v5, 7, v135
	v_lshlrev_b32_e32 v140, 4, v1
	v_bitop3_b32 v1, v132, v6, 4 bitop3:0x36
	v_bitop3_b32 v0, v0, 7, v10 bitop3:0x48
	s_waitcnt vmcnt(0)
	v_add3_u32 v139, s8, v4, v5
	v_lshlrev_b32_e32 v138, 4, v1
	v_lshl_add_u64 v[4:5], s[0:1], 0, v[2:3]
	v_lshlrev_b32_e32 v6, 4, v0
	v_lshl_add_u64 v[0:1], v[2:3], 0, s[64:65]
	v_or_b32_e32 v4, v4, v6
	v_or_b32_e32 v0, v0, v6
	v_lshl_add_u64 v[128:129], s[72:73], 0, v[4:5]
	v_lshl_add_u64 v[130:131], s[72:73], 0, v[0:1]
	s_mov_b64 s[4:5], 0
	s_mov_b32 s60, s1
	v_mov_b32_e32 v20, 0
	v_mov_b32_e32 v21, v133
	v_mov_b32_e32 v22, v133
	v_mov_b32_e32 v23, v133
	v_mov_b32_e32 v56, 0
	v_mov_b32_e32 v57, v133
	v_mov_b32_e32 v58, v133
	v_mov_b32_e32 v59, v133
	v_mov_b32_e32 v0, 0
	v_mov_b32_e32 v1, v133
	v_mov_b32_e32 v2, v133
	v_mov_b32_e32 v3, v133
	v_mov_b32_e32 v32, 0
	v_mov_b32_e32 v33, v133
	v_mov_b32_e32 v34, v133
	v_mov_b32_e32 v35, v133
	v_mov_b32_e32 v64, 0
	v_mov_b32_e32 v65, v133
	v_mov_b32_e32 v66, v133
	v_mov_b32_e32 v67, v133
	v_mov_b32_e32 v68, 0
	v_mov_b32_e32 v69, v133
	v_mov_b32_e32 v70, v133
	v_mov_b32_e32 v71, v133
	v_mov_b32_e32 v72, 0
	v_mov_b32_e32 v73, v133
	v_mov_b32_e32 v74, v133
	v_mov_b32_e32 v75, v133
	v_mov_b32_e32 v76, 0
	v_mov_b32_e32 v77, v133
	v_mov_b32_e32 v78, v133
	v_mov_b32_e32 v79, v133
	v_mov_b32_e32 v4, 0
	v_mov_b32_e32 v5, v133
	v_mov_b32_e32 v6, v133
	v_mov_b32_e32 v7, v133
	v_mov_b32_e32 v36, 0
	v_mov_b32_e32 v37, v133
	v_mov_b32_e32 v38, v133
	v_mov_b32_e32 v39, v133
	v_mov_b32_e32 v8, 0
	v_mov_b32_e32 v9, v133
	v_mov_b32_e32 v10, v133
	v_mov_b32_e32 v11, v133
	v_mov_b32_e32 v40, 0
	v_mov_b32_e32 v41, v133
	v_mov_b32_e32 v42, v133
	v_mov_b32_e32 v43, v133
	v_mov_b32_e32 v80, 0
	v_mov_b32_e32 v81, v133
	v_mov_b32_e32 v82, v133
	v_mov_b32_e32 v83, v133
	v_mov_b32_e32 v84, 0
	v_mov_b32_e32 v85, v133
	v_mov_b32_e32 v86, v133
	v_mov_b32_e32 v87, v133
	v_mov_b32_e32 v88, 0
	v_mov_b32_e32 v89, v133
	v_mov_b32_e32 v90, v133
	v_mov_b32_e32 v91, v133
	v_mov_b32_e32 v92, 0
	v_mov_b32_e32 v93, v133
	v_mov_b32_e32 v94, v133
	v_mov_b32_e32 v95, v133
	v_mov_b32_e32 v12, 0
	v_mov_b32_e32 v13, v133
	v_mov_b32_e32 v14, v133
	v_mov_b32_e32 v15, v133
	v_mov_b32_e32 v44, 0
	v_mov_b32_e32 v45, v133
	v_mov_b32_e32 v46, v133
	v_mov_b32_e32 v47, v133
	v_mov_b32_e32 v16, 0
	v_mov_b32_e32 v17, v133
	v_mov_b32_e32 v18, v133
	v_mov_b32_e32 v19, v133
	v_mov_b32_e32 v48, 0
	v_mov_b32_e32 v49, v133
	v_mov_b32_e32 v50, v133
	v_mov_b32_e32 v51, v133
	v_mov_b32_e32 v96, 0
	v_mov_b32_e32 v97, v133
	v_mov_b32_e32 v98, v133
	v_mov_b32_e32 v99, v133
	v_mov_b32_e32 v100, 0
	v_mov_b32_e32 v101, v133
	v_mov_b32_e32 v102, v133
	v_mov_b32_e32 v103, v133
	v_mov_b32_e32 v104, 0
	v_mov_b32_e32 v105, v133
	v_mov_b32_e32 v106, v133
	v_mov_b32_e32 v107, v133
	v_mov_b32_e32 v108, 0
	v_mov_b32_e32 v109, v133
	v_mov_b32_e32 v110, v133
	v_mov_b32_e32 v111, v133
	v_mov_b32_e32 v24, 0
	v_mov_b32_e32 v25, v133
	v_mov_b32_e32 v26, v133
	v_mov_b32_e32 v27, v133
	v_mov_b32_e32 v52, 0
	v_mov_b32_e32 v53, v133
	v_mov_b32_e32 v54, v133
	v_mov_b32_e32 v55, v133
	v_mov_b32_e32 v28, 0
	v_mov_b32_e32 v29, v133
	v_mov_b32_e32 v30, v133
	v_mov_b32_e32 v31, v133
	v_mov_b32_e32 v60, 0
	v_mov_b32_e32 v61, v133
	v_mov_b32_e32 v62, v133
	v_mov_b32_e32 v63, v133
	v_mov_b32_e32 v112, 0
	v_mov_b32_e32 v113, v133
	v_mov_b32_e32 v114, v133
	v_mov_b32_e32 v115, v133
	v_mov_b32_e32 v116, 0
	v_mov_b32_e32 v117, v133
	v_mov_b32_e32 v118, v133
	v_mov_b32_e32 v119, v133
	v_mov_b32_e32 v120, 0
	v_mov_b32_e32 v121, v133
	v_mov_b32_e32 v122, v133
	v_mov_b32_e32 v123, v133
	v_mov_b32_e32 v124, 0
	v_mov_b32_e32 v125, v133
	v_mov_b32_e32 v126, v133
	v_mov_b32_e32 v127, v133
	s_waitcnt vmcnt(0) lgkmcnt(0)
	s_barrier
	v_readfirstlane_b32 s64, v141
	v_readfirstlane_b32 s65, v142
	s_and_b32 s68, s60, 0x8000
	s_xor_b32 s69, s68, 0x8000
	v_add3_u32 v143, v137, v140, s68
	v_add3_u32 v157, v139, v140, s68
	ds_read_b128 v[174:177], v143
	ds_read_b128 v[178:181], v143 offset:2048
	ds_read_b128 v[182:185], v143 offset:4096
	ds_read_b128 v[144:147], v143 offset:6144
	ds_read_b128 v[158:161], v157
	ds_read_b128 v[162:165], v157 offset:2048
	ds_read_b128 v[166:169], v157 offset:4096
	ds_read_b128 v[170:173], v157 offset:6144
	s_add_i32 s70, s64, s69
	s_add_i32 s71, s65, s69
	s_add_u32 s66, s4, s36
	s_addc_u32 s67, s5, s37
	s_add_i32 m0, s70, 0x0
	v_lshl_add_u64 v[242:243], v[128:129], 0, s[66:67]
	global_load_lds_dwordx4 v[242:243], off
	s_add_u32 s66, s4, s38
	s_addc_u32 s67, s5, s39
	s_add_i32 m0, s71, 0x0
	v_lshl_add_u64 v[242:243], v[130:131], 0, s[66:67]
	global_load_lds_dwordx4 v[242:243], off
	s_add_u32 s66, s4, s40
	s_addc_u32 s67, s5, s41
	s_add_i32 m0, s70, 0x2000
	v_lshl_add_u64 v[242:243], v[128:129], 0, s[66:67]
	global_load_lds_dwordx4 v[242:243], off
	s_add_u32 s66, s4, s42
	s_addc_u32 s67, s5, s43
	s_add_i32 m0, s71, 0x2000
	v_lshl_add_u64 v[242:243], v[130:131], 0, s[66:67]
	global_load_lds_dwordx4 v[242:243], off
	s_add_u32 s66, s4, s44
	s_addc_u32 s67, s5, s45
	s_add_i32 m0, s70, 0x4000
	v_lshl_add_u64 v[242:243], v[128:129], 0, s[66:67]
	global_load_lds_dwordx4 v[242:243], off
	s_add_u32 s66, s4, s48
	s_addc_u32 s67, s5, s49
	s_add_i32 m0, s71, 0x4000
	v_lshl_add_u64 v[242:243], v[130:131], 0, s[66:67]
	global_load_lds_dwordx4 v[242:243], off
	s_add_u32 s66, s4, s50
	s_addc_u32 s67, s5, s51
	s_add_i32 m0, s70, 0x6000
	v_lshl_add_u64 v[242:243], v[128:129], 0, s[66:67]
	global_load_lds_dwordx4 v[242:243], off
	s_add_u32 s66, s4, s54
	s_addc_u32 s67, s5, s55
	s_add_i32 m0, s71, 0x6000
	v_lshl_add_u64 v[242:243], v[130:131], 0, s[66:67]
	global_load_lds_dwordx4 v[242:243], off
.LBB0_621:
	s_and_b32 s68, s60, 0x8000
	s_add_i32 s60, s60, 0x8000
	v_add3_u32 v143, v137, v138, s68
	v_add3_u32 v157, v139, v140, s68
	v_add3_u32 v186, v139, v138, s68
	s_waitcnt lgkmcnt(3)
	v_mfma_f32_16x16x32_bf16 v[124:127], v[174:177], v[158:161], v[124:127]
	v_mfma_f32_16x16x32_bf16 v[108:111], v[178:181], v[158:161], v[108:111]
	v_mfma_f32_16x16x32_bf16 v[92:95], v[182:185], v[158:161], v[92:95]
	v_mfma_f32_16x16x32_bf16 v[76:79], v[144:147], v[158:161], v[76:79]
	ds_read_b128 v[158:161], v157 offset:16384
	ds_read_b128 v[148:151], v143
	s_waitcnt lgkmcnt(4)
	v_mfma_f32_16x16x32_bf16 v[120:123], v[174:177], v[162:165], v[120:123]
	v_mfma_f32_16x16x32_bf16 v[104:107], v[178:181], v[162:165], v[104:107]
	v_mfma_f32_16x16x32_bf16 v[88:91], v[182:185], v[162:165], v[88:91]
	v_mfma_f32_16x16x32_bf16 v[72:75], v[144:147], v[162:165], v[72:75]
	ds_read_b128 v[162:165], v157 offset:18432
	ds_read_b128 v[152:155], v143 offset:2048
	s_waitcnt lgkmcnt(5)
	v_mfma_f32_16x16x32_bf16 v[116:119], v[174:177], v[166:169], v[116:119]
	v_mfma_f32_16x16x32_bf16 v[100:103], v[178:181], v[166:169], v[100:103]
	v_mfma_f32_16x16x32_bf16 v[84:87], v[182:185], v[166:169], v[84:87]
	v_mfma_f32_16x16x32_bf16 v[68:71], v[144:147], v[166:169], v[68:71]
	ds_read_b128 v[166:169], v157 offset:20480
	ds_read_b128 v[244:247], v143 offset:4096
	s_waitcnt lgkmcnt(6)
	v_mfma_f32_16x16x32_bf16 v[112:115], v[174:177], v[170:173], v[112:115]
	v_mfma_f32_16x16x32_bf16 v[96:99], v[178:181], v[170:173], v[96:99]
	v_mfma_f32_16x16x32_bf16 v[80:83], v[182:185], v[170:173], v[80:83]
	v_mfma_f32_16x16x32_bf16 v[64:67], v[144:147], v[170:173], v[64:67]
	ds_read_b128 v[170:173], v157 offset:22528
	ds_read_b128 v[248:251], v143 offset:6144
	s_waitcnt lgkmcnt(7)
	v_mfma_f32_16x16x32_bf16 v[60:63], v[174:177], v[158:161], v[60:63]
	v_mfma_f32_16x16x32_bf16 v[48:51], v[178:181], v[158:161], v[48:51]
	v_mfma_f32_16x16x32_bf16 v[40:43], v[182:185], v[158:161], v[40:43]
	v_mfma_f32_16x16x32_bf16 v[32:35], v[144:147], v[158:161], v[32:35]
	ds_read_b128 v[158:161], v186
	s_waitcnt lgkmcnt(6)
	v_mfma_f32_16x16x32_bf16 v[28:31], v[174:177], v[162:165], v[28:31]
	v_mfma_f32_16x16x32_bf16 v[16:19], v[178:181], v[162:165], v[16:19]
	v_mfma_f32_16x16x32_bf16 v[8:11], v[182:185], v[162:165], v[8:11]
	v_mfma_f32_16x16x32_bf16 v[0:3], v[144:147], v[162:165], v[0:3]
	ds_read_b128 v[162:165], v186 offset:2048
	s_waitcnt lgkmcnt(5)
	v_mfma_f32_16x16x32_bf16 v[52:55], v[174:177], v[166:169], v[52:55]
	v_mfma_f32_16x16x32_bf16 v[44:47], v[178:181], v[166:169], v[44:47]
	v_mfma_f32_16x16x32_bf16 v[36:39], v[182:185], v[166:169], v[36:39]
	v_mfma_f32_16x16x32_bf16 v[56:59], v[144:147], v[166:169], v[56:59]
	ds_read_b128 v[166:169], v186 offset:4096
	s_waitcnt lgkmcnt(4)
	v_mfma_f32_16x16x32_bf16 v[24:27], v[174:177], v[170:173], v[24:27]
	v_mfma_f32_16x16x32_bf16 v[12:15], v[178:181], v[170:173], v[12:15]
	v_mfma_f32_16x16x32_bf16 v[4:7], v[182:185], v[170:173], v[4:7]
	v_mfma_f32_16x16x32_bf16 v[20:23], v[144:147], v[170:173], v[20:23]
	ds_read_b128 v[170:173], v186 offset:6144
	s_waitcnt lgkmcnt(3)
	v_mfma_f32_16x16x32_bf16 v[124:127], v[148:151], v[158:161], v[124:127]
	v_mfma_f32_16x16x32_bf16 v[108:111], v[152:155], v[158:161], v[108:111]
	v_mfma_f32_16x16x32_bf16 v[92:95], v[244:247], v[158:161], v[92:95]
	v_mfma_f32_16x16x32_bf16 v[76:79], v[248:251], v[158:161], v[76:79]
	ds_read_b128 v[158:161], v186 offset:16384
	s_waitcnt lgkmcnt(3)
	v_mfma_f32_16x16x32_bf16 v[120:123], v[148:151], v[162:165], v[120:123]
	v_mfma_f32_16x16x32_bf16 v[104:107], v[152:155], v[162:165], v[104:107]
	v_mfma_f32_16x16x32_bf16 v[88:91], v[244:247], v[162:165], v[88:91]
	v_mfma_f32_16x16x32_bf16 v[72:75], v[248:251], v[162:165], v[72:75]
	ds_read_b128 v[162:165], v186 offset:18432
	s_waitcnt lgkmcnt(3)
	v_mfma_f32_16x16x32_bf16 v[116:119], v[148:151], v[166:169], v[116:119]
	v_mfma_f32_16x16x32_bf16 v[100:103], v[152:155], v[166:169], v[100:103]
	v_mfma_f32_16x16x32_bf16 v[84:87], v[244:247], v[166:169], v[84:87]
	v_mfma_f32_16x16x32_bf16 v[68:71], v[248:251], v[166:169], v[68:71]
	ds_read_b128 v[166:169], v186 offset:20480
	s_waitcnt lgkmcnt(3)
	v_mfma_f32_16x16x32_bf16 v[112:115], v[148:151], v[170:173], v[112:115]
	v_mfma_f32_16x16x32_bf16 v[96:99], v[152:155], v[170:173], v[96:99]
	v_mfma_f32_16x16x32_bf16 v[80:83], v[244:247], v[170:173], v[80:83]
	v_mfma_f32_16x16x32_bf16 v[64:67], v[248:251], v[170:173], v[64:67]
	ds_read_b128 v[170:173], v186 offset:22528
	s_waitcnt lgkmcnt(3)
	v_mfma_f32_16x16x32_bf16 v[60:63], v[148:151], v[158:161], v[60:63]
	v_mfma_f32_16x16x32_bf16 v[48:51], v[152:155], v[158:161], v[48:51]
	v_mfma_f32_16x16x32_bf16 v[40:43], v[244:247], v[158:161], v[40:43]
	v_mfma_f32_16x16x32_bf16 v[32:35], v[248:251], v[158:161], v[32:35]
	s_add_u32 s4, s4, 0x80
	s_addc_u32 s5, s5, 0
	s_cmpk_eq_i32 s4, 0xf80
	s_waitcnt vmcnt(0) lgkmcnt(0)
	s_barrier
	s_cbranch_scc1 .Lgemm_621_exit
	s_xor_b32 s69, s68, 0x8000
	v_add3_u32 v143, v137, v140, s69
	v_add3_u32 v157, v139, v140, s69
	ds_read_b128 v[174:177], v143
	ds_read_b128 v[178:181], v143 offset:2048
	ds_read_b128 v[182:185], v143 offset:4096
	ds_read_b128 v[144:147], v143 offset:6144
	ds_read_b128 v[158:161], v157
	s_add_i32 s70, s64, s68
	s_add_i32 s71, s65, s68
	s_add_u32 s66, s4, s36
	s_addc_u32 s67, s5, s37
	s_add_i32 m0, s70, 0x0
	v_lshl_add_u64 v[242:243], v[128:129], 0, s[66:67]
	global_load_lds_dwordx4 v[242:243], off
	s_add_u32 s66, s4, s38
	s_addc_u32 s67, s5, s39
	s_add_i32 m0, s71, 0x0
	v_lshl_add_u64 v[242:243], v[130:131], 0, s[66:67]
	global_load_lds_dwordx4 v[242:243], off
	v_mfma_f32_16x16x32_bf16 v[28:31], v[148:151], v[162:165], v[28:31]
	v_mfma_f32_16x16x32_bf16 v[16:19], v[152:155], v[162:165], v[16:19]
	v_mfma_f32_16x16x32_bf16 v[8:11], v[244:247], v[162:165], v[8:11]
	v_mfma_f32_16x16x32_bf16 v[0:3], v[248:251], v[162:165], v[0:3]
	ds_read_b128 v[162:165], v157 offset:2048
	s_add_u32 s66, s4, s40
	s_addc_u32 s67, s5, s41
	s_add_i32 m0, s70, 0x2000
	v_lshl_add_u64 v[242:243], v[128:129], 0, s[66:67]
	global_load_lds_dwordx4 v[242:243], off
	s_add_u32 s66, s4, s42
	s_addc_u32 s67, s5, s43
	s_add_i32 m0, s71, 0x2000
	v_lshl_add_u64 v[242:243], v[130:131], 0, s[66:67]
	global_load_lds_dwordx4 v[242:243], off
	v_mfma_f32_16x16x32_bf16 v[52:55], v[148:151], v[166:169], v[52:55]
	v_mfma_f32_16x16x32_bf16 v[44:47], v[152:155], v[166:169], v[44:47]
	v_mfma_f32_16x16x32_bf16 v[36:39], v[244:247], v[166:169], v[36:39]
	v_mfma_f32_16x16x32_bf16 v[56:59], v[248:251], v[166:169], v[56:59]
	ds_read_b128 v[166:169], v157 offset:4096
	s_add_u32 s66, s4, s44
	s_addc_u32 s67, s5, s45
	s_add_i32 m0, s70, 0x4000
	v_lshl_add_u64 v[242:243], v[128:129], 0, s[66:67]
	global_load_lds_dwordx4 v[242:243], off
	s_add_u32 s66, s4, s48
	s_addc_u32 s67, s5, s49
	s_add_i32 m0, s71, 0x4000
	v_lshl_add_u64 v[242:243], v[130:131], 0, s[66:67]
	global_load_lds_dwordx4 v[242:243], off
	v_mfma_f32_16x16x32_bf16 v[24:27], v[148:151], v[170:173], v[24:27]
	v_mfma_f32_16x16x32_bf16 v[12:15], v[152:155], v[170:173], v[12:15]
	v_mfma_f32_16x16x32_bf16 v[4:7], v[244:247], v[170:173], v[4:7]
	v_mfma_f32_16x16x32_bf16 v[20:23], v[248:251], v[170:173], v[20:23]
	ds_read_b128 v[170:173], v157 offset:6144
	s_add_u32 s66, s4, s50
	s_addc_u32 s67, s5, s51
	s_add_i32 m0, s70, 0x6000
	v_lshl_add_u64 v[242:243], v[128:129], 0, s[66:67]
	global_load_lds_dwordx4 v[242:243], off
	s_add_u32 s66, s4, s54
	s_addc_u32 s67, s5, s55
	s_add_i32 m0, s71, 0x6000
	v_lshl_add_u64 v[242:243], v[130:131], 0, s[66:67]
	global_load_lds_dwordx4 v[242:243], off
	s_branch .LBB0_621
.Lgemm_621_exit:
	v_mfma_f32_16x16x32_bf16 v[28:31], v[148:151], v[162:165], v[28:31]
	v_mfma_f32_16x16x32_bf16 v[16:19], v[152:155], v[162:165], v[16:19]
	v_mfma_f32_16x16x32_bf16 v[8:11], v[244:247], v[162:165], v[8:11]
	v_mfma_f32_16x16x32_bf16 v[0:3], v[248:251], v[162:165], v[0:3]
	v_mfma_f32_16x16x32_bf16 v[52:55], v[148:151], v[166:169], v[52:55]
	v_mfma_f32_16x16x32_bf16 v[44:47], v[152:155], v[166:169], v[44:47]
	v_mfma_f32_16x16x32_bf16 v[36:39], v[244:247], v[166:169], v[36:39]
	v_mfma_f32_16x16x32_bf16 v[56:59], v[248:251], v[166:169], v[56:59]
	v_mfma_f32_16x16x32_bf16 v[24:27], v[148:151], v[170:173], v[24:27]
	v_mfma_f32_16x16x32_bf16 v[12:15], v[152:155], v[170:173], v[12:15]
	v_mfma_f32_16x16x32_bf16 v[4:7], v[244:247], v[170:173], v[4:7]
	v_mfma_f32_16x16x32_bf16 v[20:23], v[248:251], v[170:173], v[20:23]
	v_add_u32_e32 v157, v137, v140
	ds_read_b128 v[128:131], v157 offset:32768
	v_add_u32_e32 v210, v139, v140
	ds_read_b128 v[148:151], v210 offset:36864
	ds_read_b128 v[152:155], v210 offset:38912
	ds_read_b128 v[140:143], v210 offset:32768
	ds_read_b128 v[144:147], v210 offset:34816
	v_add_u32_e32 v139, v139, v138
	s_lshr_b32 s4, s63, 3
	s_lshl_b32 s60, s62, 21
	s_waitcnt lgkmcnt(2)
	v_mfma_f32_16x16x32_bf16 v[158:161], v[128:131], v[152:155], v[112:115]
	s_lshl_b32 s86, s62, 14
	s_mul_i32 s4, s4, 0xc000
	s_add_u32 s4, s72, s4
	ds_read_b128 v[112:115], v157 offset:34816
	s_waitcnt lgkmcnt(2)
	v_mfma_f32_16x16x32_bf16 v[124:127], v[128:131], v[140:143], v[124:127]
	s_addc_u32 s5, s73, 0
	s_lshl_b64 s[62:63], s[58:59], 2
	s_add_u32 s4, s4, s62
	s_waitcnt lgkmcnt(0)
	v_mfma_f32_16x16x32_bf16 v[162:165], v[112:115], v[140:143], v[108:111]
	s_addc_u32 s5, s5, s63
	s_add_u32 s64, s4, 0x4000
	s_addc_u32 s65, s5, 0
	v_mfma_f32_16x16x32_bf16 v[166:169], v[112:115], v[144:147], v[104:107]
	s_nop 2
	ds_read_b128 v[104:107], v157 offset:38912
	ds_read_b128 v[108:111], v157 offset:36864
	s_add_u32 s66, s46, s62
	s_addc_u32 s67, s47, s63
	s_waitcnt lgkmcnt(0)
	v_mfma_f32_16x16x32_bf16 v[174:177], v[108:111], v[144:147], v[88:91]
	s_lshl_b32 s70, s61, 1
	s_nop 1
	v_add_u32_e32 v88, v137, v138
	s_ashr_i32 s71, s70, 31
	v_mfma_f32_16x16x32_bf16 v[120:123], v[128:131], v[144:147], v[120:123]
	s_add_u32 s68, s4, 0x8000
	s_addc_u32 s69, s5, 0
	s_lshl_b64 s[58:59], s[58:59], 1
	v_mfma_f32_16x16x32_bf16 v[170:173], v[108:111], v[140:143], v[92:95]
	s_mov_b32 s61, s1
	s_lshl_b64 s[70:71], s[70:71], 2
	v_mfma_f32_16x16x32_bf16 v[178:181], v[108:111], v[148:151], v[84:87]
	v_mfma_f32_16x16x32_bf16 v[182:185], v[108:111], v[152:155], v[80:83]
	s_nop 2
	ds_read_b128 v[80:83], v139 offset:51200
	ds_read_b128 v[186:189], v139 offset:49152
	ds_read_b128 v[190:193], v139 offset:38912
	ds_read_b128 v[194:197], v139 offset:36864
	ds_read_b128 v[198:201], v139 offset:34816
	ds_read_b128 v[202:205], v139 offset:32768
	v_mfma_f32_16x16x32_bf16 v[140:143], v[104:107], v[140:143], v[76:79]
	v_mfma_f32_16x16x32_bf16 v[144:147], v[104:107], v[144:147], v[72:75]
	s_nop 2
	ds_read_b128 v[72:75], v88 offset:38912
	ds_read_b128 v[76:79], v88 offset:36864
	ds_read_b128 v[84:87], v88 offset:34816
	ds_read_b128 v[92:95], v88 offset:32768
	v_mfma_f32_16x16x32_bf16 v[116:119], v[128:131], v[148:151], v[116:119]
	v_mfma_f32_16x16x32_bf16 v[100:103], v[112:115], v[148:151], v[100:103]
	v_mfma_f32_16x16x32_bf16 v[96:99], v[112:115], v[152:155], v[96:99]
	s_waitcnt lgkmcnt(0)
	v_mfma_f32_16x16x32_bf16 v[218:221], v[92:95], v[202:205], v[124:127]
	v_mfma_f32_16x16x32_bf16 v[120:123], v[92:95], v[198:201], v[120:123]
	s_nop 1
	v_lshl_or_b32 v126, v132, 2, v136
	v_mad_u32_u24 v124, v134, s9, 0
	v_lshlrev_b32_e32 v125, 2, v135
	v_mfma_f32_16x16x32_bf16 v[116:119], v[92:95], v[194:197], v[116:119]
	v_mul_lo_u32 v126, v126, s14
	v_add3_u32 v126, v124, v125, v126
	v_add_u32_e32 v127, 0x400, v126
	v_mfma_f32_16x16x32_bf16 v[134:137], v[92:95], v[190:193], v[158:161]
	v_add_u32_e32 v138, 0x4800, v126
	v_mov_b32_e32 v125, v156
	v_mfma_f32_16x16x32_bf16 v[148:151], v[104:107], v[148:151], v[68:71]
	s_nop 2
	ds_read_b128 v[68:71], v210 offset:55296
	ds_read_b128 v[206:209], v210 offset:53248
	ds_read_b128 v[88:91], v210 offset:51200
	ds_read_b128 v[210:213], v210 offset:49152
	v_mfma_f32_16x16x32_bf16 v[152:155], v[104:107], v[152:155], v[64:67]
	ds_read_b128 v[214:217], v139 offset:53248
	s_nop 1
	ds_read_b128 v[64:67], v139 offset:55296
	s_waitcnt vmcnt(0)
	s_waitcnt lgkmcnt(0)
	s_barrier
	ds_write2_b32 v126, v218, v120 offset1:16
	ds_write2_b32 v126, v219, v121 offset0:136 offset1:152
	ds_write2_b32 v127, v220, v122 offset0:16 offset1:32
	v_mfma_f32_16x16x32_bf16 v[158:161], v[84:87], v[202:205], v[162:165]
	ds_write2_b32 v127, v221, v123 offset0:152 offset1:168
	ds_write2_b32 v126, v116, v134 offset0:32 offset1:48
	ds_write2_b32 v126, v117, v135 offset0:168 offset1:184
	ds_write2_b32 v127, v118, v136 offset0:48 offset1:64
	ds_write2_b32 v127, v119, v137 offset0:184 offset1:200
	v_add_u32_e32 v134, 0x2000, v126
	v_mfma_f32_16x16x32_bf16 v[120:123], v[84:87], v[198:201], v[166:169]
	v_add_u32_e32 v135, 0x2400, v126
	v_add_u32_e32 v136, 0x2800, v126
	v_add_u32_e32 v137, 0x4400, v126
	v_mfma_f32_16x16x32_bf16 v[100:103], v[84:87], v[194:197], v[100:103]
	v_add_u32_e32 v139, 0x6400, v126
	s_nop 2
	ds_write2_b32 v134, v158, v120 offset0:128 offset1:144
	ds_write2_b32 v135, v159, v121 offset0:8 offset1:24
	v_mfma_f32_16x16x32_bf16 v[96:99], v[84:87], v[190:193], v[96:99]
	ds_write2_b32 v135, v160, v122 offset0:144 offset1:160
	ds_write2_b32 v136, v161, v123 offset0:24 offset1:40
	s_nop 5
	ds_write2_b32 v134, v100, v96 offset0:160 offset1:176
	ds_write2_b32 v135, v101, v97 offset0:40 offset1:56
	ds_write2_b32 v135, v102, v98 offset0:176 offset1:192
	v_mfma_f32_16x16x32_bf16 v[116:119], v[76:79], v[202:205], v[170:173]
	ds_write2_b32 v136, v103, v99 offset0:56 offset1:72
	v_mfma_f32_16x16x32_bf16 v[120:123], v[76:79], v[198:201], v[174:177]
	v_mfma_f32_16x16x32_bf16 v[96:99], v[76:79], v[194:197], v[178:181]
	v_mfma_f32_16x16x32_bf16 v[100:103], v[76:79], v[190:193], v[182:185]
	s_nop 5
	ds_write2_b32 v137, v116, v120 offset1:16
	ds_write2_b32 v137, v117, v121 offset0:136 offset1:152
	ds_write2_b32 v138, v118, v122 offset0:16 offset1:32
	ds_write2_b32 v138, v119, v123 offset0:152 offset1:168
	ds_write2_b32 v137, v96, v100 offset0:32 offset1:48
	ds_write2_b32 v137, v97, v101 offset0:168 offset1:184
	v_mfma_f32_16x16x32_bf16 v[116:119], v[72:75], v[202:205], v[140:143]
	ds_write2_b32 v138, v98, v102 offset0:48 offset1:64
	ds_write2_b32 v138, v99, v103 offset0:184 offset1:200
	s_nop 0
	v_add_u32_e32 v140, 0x6800, v126
	v_mfma_f32_16x16x32_bf16 v[96:99], v[72:75], v[198:201], v[144:147]
	v_add_u32_e32 v141, 0x6c00, v126
	v_mfma_f32_16x16x32_bf16 v[100:103], v[72:75], v[194:197], v[148:151]
	v_mfma_f32_16x16x32_bf16 v[60:63], v[128:131], v[210:213], v[60:63]
	s_nop 4
	ds_write2_b32 v139, v116, v96 offset0:128 offset1:144
	ds_write2_b32 v140, v117, v97 offset0:8 offset1:24
	ds_write2_b32 v140, v118, v98 offset0:144 offset1:160
	ds_write2_b32 v141, v119, v99 offset0:24 offset1:40
	v_mfma_f32_16x16x32_bf16 v[96:99], v[72:75], v[190:193], v[152:155]
	s_nop 7
	ds_write2_b32 v139, v100, v96 offset0:160 offset1:176
	ds_write2_b32 v140, v101, v97 offset0:40 offset1:56
	ds_write2_b32 v140, v102, v98 offset0:176 offset1:192
	ds_write2_b32 v141, v103, v99 offset0:56 offset1:72
	s_waitcnt lgkmcnt(0)
	s_barrier
	v_mfma_f32_16x16x32_bf16 v[100:103], v[128:131], v[206:209], v[52:55]
	v_and_b32_e32 v132, 31, v125
	v_lshlrev_b32_e32 v124, 4, v132
	s_nop 0
	global_load_dwordx4 v[52:55], v124, s[68:69]
	global_load_dwordx4 v[116:119], v124, s[66:67]
	global_load_dwordx4 v[96:99], v124, s[64:65]
	v_ashrrev_i32_e32 v146, 5, v125
	v_ashrrev_i32_e32 v147, 31, v146
	v_cmp_eq_u32_e64 s[4:5], 0, v132
	v_mfma_f32_16x16x32_bf16 v[120:123], v[104:107], v[206:209], v[56:59]
	v_lshlrev_b32_e32 v132, 3, v132
	s_waitcnt vmcnt(2)
	v_add_f32_e32 v52, 1.0, v52
	s_waitcnt vmcnt(1)
	v_mul_f32_e32 v142, v116, v52
	v_add_f32_e32 v52, 1.0, v53
	v_mul_f32_e32 v143, v117, v52
	v_add_f32_e32 v52, 1.0, v54
	v_mul_f32_e32 v144, v118, v52
	v_add_f32_e32 v52, 1.0, v55
	v_mul_f32_e32 v145, v119, v52
	v_lshlrev_b64 v[52:53], 12, v[146:147]
	v_lshl_add_u64 v[56:57], s[0:1], 0, v[52:53]
	v_mfma_f32_16x16x32_bf16 v[44:47], v[112:115], v[206:209], v[44:47]
	v_mfma_f32_16x16x32_bf16 v[52:55], v[92:95], v[186:189], v[60:63]
	s_nop 2
	v_lshl_add_u64 v[60:61], v[56:57], 0, v[132:133]
	v_mfma_f32_16x16x32_bf16 v[56:59], v[92:95], v[214:217], v[100:103]
	s_nop 2
	v_lshl_add_u64 v[100:101], v[60:61], 0, s[58:59]
	v_lshlrev_b64 v[60:61], 13, v[146:147]
	v_lshl_add_u64 v[60:61], s[60:61], 0, v[60:61]
	v_or_b32_e32 v60, v60, v124
	v_lshl_add_u64 v[116:117], v[60:61], 0, s[62:63]
	v_mfma_f32_16x16x32_bf16 v[60:63], v[84:87], v[214:217], v[44:47]
	v_lshl_add_u64 v[102:103], s[30:31], 0, v[116:117]
	v_lshl_add_u64 v[116:117], s[52:53], 0, v[116:117]
	s_nop 0
	v_mad_u64_u32 v[44:45], s[76:77], v146, s14, v[124:125]
	v_mfma_f32_16x16x32_bf16 v[48:51], v[112:115], v[210:213], v[48:51]
	s_add_u32 s76, s86, s70
	s_addc_u32 s77, 0, s71
	v_and_b32_e32 v45, 16, v125
	v_mfma_f32_16x16x32_bf16 v[40:43], v[108:111], v[210:213], v[40:43]
	s_add_u32 s76, s76, 0x1a290800
	v_add3_u32 v132, v44, v45, 0
	v_lshlrev_b64 v[44:45], 6, v[146:147]
	v_mfma_f32_16x16x32_bf16 v[36:39], v[108:111], v[206:209], v[36:39]
	s_addc_u32 s77, s77, 0
	v_lshl_add_u64 v[118:119], s[76:77], 0, v[44:45]
	s_mov_b64 s[76:77], 0
	v_mfma_f32_16x16x32_bf16 v[32:35], v[104:107], v[210:213], v[32:35]
	v_mfma_f32_16x16x32_bf16 v[48:51], v[84:87], v[186:189], v[48:51]
	v_mfma_f32_16x16x32_bf16 v[40:43], v[76:79], v[186:189], v[40:43]
	v_mfma_f32_16x16x32_bf16 v[36:39], v[76:79], v[214:217], v[36:39]
	v_mfma_f32_16x16x32_bf16 v[32:35], v[72:75], v[186:189], v[32:35]
	v_mfma_f32_16x16x32_bf16 v[44:47], v[72:75], v[214:217], v[120:123]
	s_branch .LBB0_624

	.amdhsa_kernel _Z4mega6Params
		.amdhsa_group_segment_fixed_size 0
		.amdhsa_private_segment_fixed_size 0
		.amdhsa_kernarg_size 424
		.amdhsa_user_sgpr_count 2
		.amdhsa_user_sgpr_dispatch_ptr 0
		.amdhsa_user_sgpr_queue_ptr 0
		.amdhsa_user_sgpr_kernarg_segment_ptr 1
		.amdhsa_user_sgpr_dispatch_id 0
		.amdhsa_user_sgpr_kernarg_preload_length 0
		.amdhsa_user_sgpr_kernarg_preload_offset 0
		.amdhsa_user_sgpr_private_segment_size 0
		.amdhsa_uses_dynamic_stack 0
		.amdhsa_enable_private_segment 0
		.amdhsa_system_sgpr_workgroup_id_x 1
		.amdhsa_system_sgpr_workgroup_id_y 0
		.amdhsa_system_sgpr_workgroup_id_z 0
		.amdhsa_system_sgpr_workgroup_info 0
		.amdhsa_system_vgpr_workitem_id 2
		.amdhsa_next_free_vgpr 256
		.amdhsa_next_free_sgpr 98
		.amdhsa_accum_offset 256
		.amdhsa_reserve_vcc 1
		.amdhsa_float_round_mode_32 0
		.amdhsa_float_round_mode_16_64 0
		.amdhsa_float_denorm_mode_32 3
		.amdhsa_float_denorm_mode_16_64 3
		.amdhsa_dx10_clamp 1
		.amdhsa_ieee_mode 1
		.amdhsa_fp16_overflow 0
		.amdhsa_tg_split 0
		.amdhsa_exception_fp_ieee_invalid_op 0
		.amdhsa_exception_fp_denorm_src 0
		.amdhsa_exception_fp_ieee_div_zero 0
		.amdhsa_exception_fp_ieee_overflow 0
		.amdhsa_exception_fp_ieee_underflow 0
		.amdhsa_exception_fp_ieee_inexact 0
		.amdhsa_exception_int_div_zero 0
	.end_amdhsa_kernel

amdhsa.kernels:
  - .agpr_count:     0
    .args:
      - .offset:         0
        .size:           168
        .value_kind:     by_value
      - .offset:         168
        .size:           4
        .value_kind:     hidden_block_count_x
      - .offset:         172
        .size:           4
        .value_kind:     hidden_block_count_y
      - .offset:         176
        .size:           4
        .value_kind:     hidden_block_count_z
      - .offset:         180
        .size:           2
        .value_kind:     hidden_group_size_x
      - .offset:         182
        .size:           2
        .value_kind:     hidden_group_size_y
      - .offset:         184
        .size:           2
        .value_kind:     hidden_group_size_z
      - .offset:         186
        .size:           2
        .value_kind:     hidden_remainder_x
      - .offset:         188
        .size:           2
        .value_kind:     hidden_remainder_y
      - .offset:         190
        .size:           2
        .value_kind:     hidden_remainder_z
      - .offset:         208
        .size:           8
        .value_kind:     hidden_global_offset_x
      - .offset:         216
        .size:           8
        .value_kind:     hidden_global_offset_y
      - .offset:         224
        .size:           8
        .value_kind:     hidden_global_offset_z
      - .offset:         232
        .size:           2
        .value_kind:     hidden_grid_dims
      - .offset:         256
        .size:           8
        .value_kind:     hidden_multigrid_sync_arg
      - .offset:         288
        .size:           4
        .value_kind:     hidden_dynamic_lds_size
    .group_segment_fixed_size: 0
    .kernarg_segment_align: 8
    .kernarg_segment_size: 424
    .language:       OpenCL C
    .language_version:
      - 2
      - 0
    .max_flat_workgroup_size: 512
    .name:           _Z4mega6Params
    .private_segment_fixed_size: 0
    .sgpr_count:     104
    .sgpr_spill_count: 8
    .symbol:         _Z4mega6Params.kd
    .uniform_work_group_size: 1
    .uses_dynamic_stack: false
    .vgpr_count:     256
    .vgpr_spill_count: 0
    .wavefront_size: 64
